# v22: LayerNorm with 8 consecutive columns per lane (16-byte bf16 stores)
# baseline (speedup 1.0000x reference)
.LBB0_790:
	s_cmp_lt_i32 s28, 8
	s_cselect_b64 s[0:1], -1, 0
	s_cmp_gt_i32 s29, 7
	s_cselect_b64 s[2:3], -1, 0
	s_and_b64 s[0:1], s[0:1], s[2:3]
	s_andn2_b64 vcc, exec, s[0:1]
	s_cbranch_vccnz .LBB0_856
	s_mov_b64 s[8:9], exec
	v_readlane_b32 s0, v254, 4
	v_lshrrev_b32_e32 v0, 6, v200
	s_lshl_b32 s3, s30, 3
	v_readfirstlane_b32 s2, v0
	v_mbcnt_lo_u32_b32 v0, -1, 0
	v_mbcnt_hi_u32_b32 v0, -1, v0
	s_add_i32 s2, s2, s0
	s_cmp_ge_i32 s2, 0x10000
	s_cbranch_scc1 .Llna1_done
	v_lshlrev_b32_e32 v1, 4, v0
	v_lshlrev_b32_e32 v0, 5, v0
	s_add_u32 s4, s36, 0
	s_addc_u32 s5, s37, 0
	s_add_u32 s6, s38, 0
	s_addc_u32 s7, s39, 0
	global_load_dwordx4 v[80:83], v0, s[4:5] offset:0
	global_load_dwordx4 v[84:87], v0, s[4:5] offset:16
	global_load_dwordx4 v[88:91], v0, s[4:5] offset:2048
	global_load_dwordx4 v[92:95], v0, s[4:5] offset:2064
	global_load_dwordx4 v[96:99], v0, s[6:7] offset:0
	global_load_dwordx4 v[100:103], v0, s[6:7] offset:16
	global_load_dwordx4 v[104:107], v0, s[6:7] offset:2048
	global_load_dwordx4 v[108:111], v0, s[6:7] offset:2064
	s_add_u32 s10, s26, 0x6000000
	s_addc_u32 s11, s27, 0
	v_mov_b32_e32 v112, 0x3727c5ac
	s_add_i32 s12, s2, s3
	s_cmp_lt_i32 s12, 0x10000
	s_cselect_b32 s13, s12, s2
	s_lshl_b32 s4, s2, 12
	s_add_u32 s4, s24, s4
	s_addc_u32 s5, s25, 0
	s_lshl_b32 s6, s13, 12
	s_add_u32 s6, s24, s6
	s_addc_u32 s7, s25, 0
	global_load_dwordx4 v[48:51], v0, s[4:5] offset:0
	global_load_dwordx4 v[52:55], v0, s[4:5] offset:16
	global_load_dwordx4 v[56:59], v0, s[4:5] offset:2048
	global_load_dwordx4 v[60:63], v0, s[4:5] offset:2064
	global_load_dwordx4 v[64:67], v0, s[6:7] offset:0
	global_load_dwordx4 v[68:71], v0, s[6:7] offset:16
	global_load_dwordx4 v[72:75], v0, s[6:7] offset:2048
	global_load_dwordx4 v[76:79], v0, s[6:7] offset:2064
	s_waitcnt vmcnt(0)
	s_branch .Llna1_enter
.Llna1_top:
	s_waitcnt vmcnt(4)
.Llna1_enter:
	s_mov_b32 s8, s2
	s_add_i32 s9, s2, s3
	v_mov_b64_e32 v[16:17], v[48:49]
	v_mov_b64_e32 v[18:19], v[50:51]
	v_mov_b64_e32 v[20:21], v[52:53]
	v_mov_b64_e32 v[22:23], v[54:55]
	v_mov_b64_e32 v[24:25], v[56:57]
	v_mov_b64_e32 v[26:27], v[58:59]
	v_mov_b64_e32 v[28:29], v[60:61]
	v_mov_b64_e32 v[30:31], v[62:63]
	v_mov_b64_e32 v[32:33], v[64:65]
	v_mov_b64_e32 v[34:35], v[66:67]
	v_mov_b64_e32 v[36:37], v[68:69]
	v_mov_b64_e32 v[38:39], v[70:71]
	v_mov_b64_e32 v[40:41], v[72:73]
	v_mov_b64_e32 v[42:43], v[74:75]
	v_mov_b64_e32 v[44:45], v[76:77]
	v_mov_b64_e32 v[46:47], v[78:79]
	s_lshl_b32 s12, s3, 1
	s_add_i32 s2, s2, s12
	s_cmp_ge_i32 s2, 0x10000
	s_cbranch_scc1 .Llna1_nopf
	s_add_i32 s12, s2, s3
	s_cmp_lt_i32 s12, 0x10000
	s_cselect_b32 s13, s12, s2
	s_lshl_b32 s4, s2, 12
	s_add_u32 s4, s24, s4
	s_addc_u32 s5, s25, 0
	s_lshl_b32 s6, s13, 12
	s_add_u32 s6, s24, s6
	s_addc_u32 s7, s25, 0
	global_load_dwordx4 v[48:51], v0, s[4:5] offset:0
	global_load_dwordx4 v[52:55], v0, s[4:5] offset:16
	global_load_dwordx4 v[56:59], v0, s[4:5] offset:2048
	global_load_dwordx4 v[60:63], v0, s[4:5] offset:2064
	global_load_dwordx4 v[64:67], v0, s[6:7] offset:0
	global_load_dwordx4 v[68:71], v0, s[6:7] offset:16
	global_load_dwordx4 v[72:75], v0, s[6:7] offset:2048
	global_load_dwordx4 v[76:79], v0, s[6:7] offset:2064
.Llna1_nopf:
	v_add_f32_e32 v113, v16, v20
	v_add_f32_e32 v114, v17, v21
	v_add_f32_e32 v115, v18, v22
	v_add_f32_e32 v116, v19, v23
	v_add_f32_e32 v117, v32, v36
	v_add_f32_e32 v118, v33, v37
	v_add_f32_e32 v119, v34, v38
	v_add_f32_e32 v120, v35, v39
	v_add_f32_e32 v113, v113, v24
	v_add_f32_e32 v113, v113, v28
	v_add_f32_e32 v114, v114, v25
	v_add_f32_e32 v114, v114, v29
	v_add_f32_e32 v115, v115, v26
	v_add_f32_e32 v115, v115, v30
	v_add_f32_e32 v116, v116, v27
	v_add_f32_e32 v116, v116, v31
	v_add_f32_e32 v117, v117, v40
	v_add_f32_e32 v117, v117, v44
	v_add_f32_e32 v118, v118, v41
	v_add_f32_e32 v118, v118, v45
	v_add_f32_e32 v119, v119, v42
	v_add_f32_e32 v119, v119, v46
	v_add_f32_e32 v120, v120, v43
	v_add_f32_e32 v120, v120, v47
	v_add_f32_e32 v113, v113, v114
	v_add_f32_e32 v115, v115, v116
	v_add_f32_e32 v117, v117, v118
	v_add_f32_e32 v119, v119, v120
	v_add_f32_e32 v113, v113, v115
	v_add_f32_e32 v117, v117, v119
	s_nop 1
	v_add_f32_dpp v113, v113, v113 quad_perm:[1,0,3,2] row_mask:0xf bank_mask:0xf
	v_add_f32_dpp v117, v117, v117 quad_perm:[1,0,3,2] row_mask:0xf bank_mask:0xf
	s_nop 1
	v_add_f32_dpp v113, v113, v113 quad_perm:[2,3,0,1] row_mask:0xf bank_mask:0xf
	v_add_f32_dpp v117, v117, v117 quad_perm:[2,3,0,1] row_mask:0xf bank_mask:0xf
	s_nop 1
	v_add_f32_dpp v113, v113, v113 row_half_mirror row_mask:0xf bank_mask:0xf
	v_add_f32_dpp v117, v117, v117 row_half_mirror row_mask:0xf bank_mask:0xf
	s_nop 1
	v_add_f32_dpp v113, v113, v113 row_mirror row_mask:0xf bank_mask:0xf
	v_add_f32_dpp v117, v117, v117 row_mirror row_mask:0xf bank_mask:0xf
	s_nop 1
	v_readlane_b32 s4, v113, 0
	v_readlane_b32 s5, v113, 16
	v_readlane_b32 s6, v113, 32
	v_readlane_b32 s7, v113, 48
	v_readlane_b32 s12, v117, 0
	v_readlane_b32 s13, v117, 16
	v_readlane_b32 s0, v117, 32
	v_readlane_b32 s1, v117, 48
	s_nop 1
	v_mov_b32_e32 v113, s4
	v_mov_b32_e32 v117, s12
	v_add_f32_e32 v113, s5, v113
	v_add_f32_e32 v117, s13, v117
	v_add_f32_e32 v113, s6, v113
	v_add_f32_e32 v117, s0, v117
	v_add_f32_e32 v113, s7, v113
	v_add_f32_e32 v117, s1, v117
	v_fmamk_f32 v16, v113, 0xba800000, v16
	v_fmamk_f32 v17, v113, 0xba800000, v17
	v_fmamk_f32 v18, v113, 0xba800000, v18
	v_fmamk_f32 v19, v113, 0xba800000, v19
	v_fmamk_f32 v20, v113, 0xba800000, v20
	v_fmamk_f32 v21, v113, 0xba800000, v21
	v_fmamk_f32 v22, v113, 0xba800000, v22
	v_fmamk_f32 v23, v113, 0xba800000, v23
	v_fmamk_f32 v24, v113, 0xba800000, v24
	v_fmamk_f32 v25, v113, 0xba800000, v25
	v_fmamk_f32 v26, v113, 0xba800000, v26
	v_fmamk_f32 v27, v113, 0xba800000, v27
	v_fmamk_f32 v28, v113, 0xba800000, v28
	v_fmamk_f32 v29, v113, 0xba800000, v29
	v_fmamk_f32 v30, v113, 0xba800000, v30
	v_fmamk_f32 v31, v113, 0xba800000, v31
	v_fmamk_f32 v32, v117, 0xba800000, v32
	v_fmamk_f32 v33, v117, 0xba800000, v33
	v_fmamk_f32 v34, v117, 0xba800000, v34
	v_fmamk_f32 v35, v117, 0xba800000, v35
	v_fmamk_f32 v36, v117, 0xba800000, v36
	v_fmamk_f32 v37, v117, 0xba800000, v37
	v_fmamk_f32 v38, v117, 0xba800000, v38
	v_fmamk_f32 v39, v117, 0xba800000, v39
	v_fmamk_f32 v40, v117, 0xba800000, v40
	v_fmamk_f32 v41, v117, 0xba800000, v41
	v_fmamk_f32 v42, v117, 0xba800000, v42
	v_fmamk_f32 v43, v117, 0xba800000, v43
	v_fmamk_f32 v44, v117, 0xba800000, v44
	v_fmamk_f32 v45, v117, 0xba800000, v45
	v_fmamk_f32 v46, v117, 0xba800000, v46
	v_fmamk_f32 v47, v117, 0xba800000, v47
	v_mul_f32_e32 v113, v16, v16
	v_mul_f32_e32 v114, v17, v17
	v_mul_f32_e32 v115, v18, v18
	v_mul_f32_e32 v116, v19, v19
	v_mul_f32_e32 v117, v32, v32
	v_mul_f32_e32 v118, v33, v33
	v_mul_f32_e32 v119, v34, v34
	v_mul_f32_e32 v120, v35, v35
	v_fmac_f32_e32 v113, v20, v20
	v_fmac_f32_e32 v113, v24, v24
	v_fmac_f32_e32 v113, v28, v28
	v_fmac_f32_e32 v114, v21, v21
	v_fmac_f32_e32 v114, v25, v25
	v_fmac_f32_e32 v114, v29, v29
	v_fmac_f32_e32 v115, v22, v22
	v_fmac_f32_e32 v115, v26, v26
	v_fmac_f32_e32 v115, v30, v30
	v_fmac_f32_e32 v116, v23, v23
	v_fmac_f32_e32 v116, v27, v27
	v_fmac_f32_e32 v116, v31, v31
	v_fmac_f32_e32 v117, v36, v36
	v_fmac_f32_e32 v117, v40, v40
	v_fmac_f32_e32 v117, v44, v44
	v_fmac_f32_e32 v118, v37, v37
	v_fmac_f32_e32 v118, v41, v41
	v_fmac_f32_e32 v118, v45, v45
	v_fmac_f32_e32 v119, v38, v38
	v_fmac_f32_e32 v119, v42, v42
	v_fmac_f32_e32 v119, v46, v46
	v_fmac_f32_e32 v120, v39, v39
	v_fmac_f32_e32 v120, v43, v43
	v_fmac_f32_e32 v120, v47, v47
	v_add_f32_e32 v113, v113, v114
	v_add_f32_e32 v115, v115, v116
	v_add_f32_e32 v117, v117, v118
	v_add_f32_e32 v119, v119, v120
	v_add_f32_e32 v113, v113, v115
	v_add_f32_e32 v117, v117, v119
	s_nop 1
	v_add_f32_dpp v113, v113, v113 quad_perm:[1,0,3,2] row_mask:0xf bank_mask:0xf
	v_add_f32_dpp v117, v117, v117 quad_perm:[1,0,3,2] row_mask:0xf bank_mask:0xf
	s_nop 1
	v_add_f32_dpp v113, v113, v113 quad_perm:[2,3,0,1] row_mask:0xf bank_mask:0xf
	v_add_f32_dpp v117, v117, v117 quad_perm:[2,3,0,1] row_mask:0xf bank_mask:0xf
	s_nop 1
	v_add_f32_dpp v113, v113, v113 row_half_mirror row_mask:0xf bank_mask:0xf
	v_add_f32_dpp v117, v117, v117 row_half_mirror row_mask:0xf bank_mask:0xf
	s_nop 1
	v_add_f32_dpp v113, v113, v113 row_mirror row_mask:0xf bank_mask:0xf
	v_add_f32_dpp v117, v117, v117 row_mirror row_mask:0xf bank_mask:0xf
	s_nop 1
	v_readlane_b32 s4, v113, 0
	v_readlane_b32 s5, v113, 16
	v_readlane_b32 s6, v113, 32
	v_readlane_b32 s7, v113, 48
	v_readlane_b32 s12, v117, 0
	v_readlane_b32 s13, v117, 16
	v_readlane_b32 s0, v117, 32
	v_readlane_b32 s1, v117, 48
	s_nop 1
	v_mov_b32_e32 v113, s4
	v_mov_b32_e32 v117, s12
	v_add_f32_e32 v113, s5, v113
	v_add_f32_e32 v117, s13, v117
	v_add_f32_e32 v113, s6, v113
	v_add_f32_e32 v117, s0, v117
	v_add_f32_e32 v113, s7, v113
	v_add_f32_e32 v117, s1, v117
	v_fmamk_f32 v113, v113, 0x3a800000, v112
	v_fmamk_f32 v117, v117, 0x3a800000, v112
	v_rsq_f32_e32 v113, v113
	v_rsq_f32_e32 v117, v117
	s_nop 0
	v_mul_f32_e32 v16, v16, v113
	v_mul_f32_e32 v17, v17, v113
	v_mul_f32_e32 v18, v18, v113
	v_mul_f32_e32 v19, v19, v113
	v_mul_f32_e32 v20, v20, v113
	v_mul_f32_e32 v21, v21, v113
	v_mul_f32_e32 v22, v22, v113
	v_mul_f32_e32 v23, v23, v113
	v_mul_f32_e32 v24, v24, v113
	v_mul_f32_e32 v25, v25, v113
	v_mul_f32_e32 v26, v26, v113
	v_mul_f32_e32 v27, v27, v113
	v_mul_f32_e32 v28, v28, v113
	v_mul_f32_e32 v29, v29, v113
	v_mul_f32_e32 v30, v30, v113
	v_mul_f32_e32 v31, v31, v113
	v_fma_f32 v16, v16, v80, v96
	v_fma_f32 v17, v17, v81, v97
	v_fma_f32 v18, v18, v82, v98
	v_fma_f32 v19, v19, v83, v99
	v_fma_f32 v20, v20, v84, v100
	v_fma_f32 v21, v21, v85, v101
	v_fma_f32 v22, v22, v86, v102
	v_fma_f32 v23, v23, v87, v103
	v_fma_f32 v24, v24, v88, v104
	v_fma_f32 v25, v25, v89, v105
	v_fma_f32 v26, v26, v90, v106
	v_fma_f32 v27, v27, v91, v107
	v_fma_f32 v28, v28, v92, v108
	v_fma_f32 v29, v29, v93, v109
	v_fma_f32 v30, v30, v94, v110
	v_fma_f32 v31, v31, v95, v111
	v_mul_f32_e32 v32, v32, v117
	v_mul_f32_e32 v33, v33, v117
	v_mul_f32_e32 v34, v34, v117
	v_mul_f32_e32 v35, v35, v117
	v_mul_f32_e32 v36, v36, v117
	v_mul_f32_e32 v37, v37, v117
	v_mul_f32_e32 v38, v38, v117
	v_mul_f32_e32 v39, v39, v117
	v_mul_f32_e32 v40, v40, v117
	v_mul_f32_e32 v41, v41, v117
	v_mul_f32_e32 v42, v42, v117
	v_mul_f32_e32 v43, v43, v117
	v_mul_f32_e32 v44, v44, v117
	v_mul_f32_e32 v45, v45, v117
	v_mul_f32_e32 v46, v46, v117
	v_mul_f32_e32 v47, v47, v117
	v_fma_f32 v32, v32, v80, v96
	v_fma_f32 v33, v33, v81, v97
	v_fma_f32 v34, v34, v82, v98
	v_fma_f32 v35, v35, v83, v99
	v_fma_f32 v36, v36, v84, v100
	v_fma_f32 v37, v37, v85, v101
	v_fma_f32 v38, v38, v86, v102
	v_fma_f32 v39, v39, v87, v103
	v_fma_f32 v40, v40, v88, v104
	v_fma_f32 v41, v41, v89, v105
	v_fma_f32 v42, v42, v90, v106
	v_fma_f32 v43, v43, v91, v107
	v_fma_f32 v44, v44, v92, v108
	v_fma_f32 v45, v45, v93, v109
	v_fma_f32 v46, v46, v94, v110
	v_fma_f32 v47, v47, v95, v111
	v_cvt_pk_bf16_f32 v16, v16, v17
	v_cvt_pk_bf16_f32 v17, v18, v19
	v_cvt_pk_bf16_f32 v18, v20, v21
	v_cvt_pk_bf16_f32 v19, v22, v23
	v_cvt_pk_bf16_f32 v20, v24, v25
	v_cvt_pk_bf16_f32 v21, v26, v27
	v_cvt_pk_bf16_f32 v22, v28, v29
	v_cvt_pk_bf16_f32 v23, v30, v31
	v_cvt_pk_bf16_f32 v32, v32, v33
	v_cvt_pk_bf16_f32 v33, v34, v35
	v_cvt_pk_bf16_f32 v34, v36, v37
	v_cvt_pk_bf16_f32 v35, v38, v39
	v_cvt_pk_bf16_f32 v36, v40, v41
	v_cvt_pk_bf16_f32 v37, v42, v43
	v_cvt_pk_bf16_f32 v38, v44, v45
	v_cvt_pk_bf16_f32 v39, v46, v47
	s_lshl_b32 s4, s8, 11
	s_add_u32 s4, s10, s4
	s_addc_u32 s5, s11, 0
	global_store_dwordx4 v1, v[16:19], s[4:5] offset:0
	global_store_dwordx4 v1, v[20:23], s[4:5] offset:1024
	s_cmp_ge_i32 s9, 0x10000
	s_cbranch_scc1 .Llna1_st1
	s_lshl_b32 s6, s9, 11
	s_add_u32 s6, s10, s6
	s_addc_u32 s7, s11, 0
	global_store_dwordx4 v1, v[32:35], s[6:7] offset:0
	global_store_dwordx4 v1, v[36:39], s[6:7] offset:1024

.LBB0_1079:
	s_cmp_lt_i32 s28, 12
	s_cselect_b64 s[0:1], -1, 0
	s_cmp_gt_i32 s29, 11
	s_cselect_b64 s[2:3], -1, 0
	s_and_b64 s[0:1], s[0:1], s[2:3]
	s_andn2_b64 vcc, exec, s[0:1]
	s_cbranch_vccnz .LBB0_1145
	s_mov_b64 s[8:9], exec
	v_readlane_b32 s0, v254, 4
	v_lshrrev_b32_e32 v0, 6, v200
	s_lshl_b32 s3, s30, 3
	v_readfirstlane_b32 s2, v0
	v_mbcnt_lo_u32_b32 v0, -1, 0
	v_mbcnt_hi_u32_b32 v0, -1, v0
	s_add_i32 s2, s2, s0
	s_cmp_ge_i32 s2, 0x10000
	s_cbranch_scc1 .Llna2_done
	v_lshlrev_b32_e32 v1, 4, v0
	v_lshlrev_b32_e32 v0, 5, v0
	s_add_u32 s4, s40, 0
	s_addc_u32 s5, s41, 0
	s_add_u32 s6, s42, 0
	s_addc_u32 s7, s43, 0
	global_load_dwordx4 v[80:83], v0, s[4:5] offset:0
	global_load_dwordx4 v[84:87], v0, s[4:5] offset:16
	global_load_dwordx4 v[88:91], v0, s[4:5] offset:2048
	global_load_dwordx4 v[92:95], v0, s[4:5] offset:2064
	global_load_dwordx4 v[96:99], v0, s[6:7] offset:0
	global_load_dwordx4 v[100:103], v0, s[6:7] offset:16
	global_load_dwordx4 v[104:107], v0, s[6:7] offset:2048
	global_load_dwordx4 v[108:111], v0, s[6:7] offset:2064
	s_add_u32 s10, s26, 0x6000000
	s_addc_u32 s11, s27, 0
	v_mov_b32_e32 v112, 0x3727c5ac
	s_add_i32 s12, s2, s3
	s_cmp_lt_i32 s12, 0x10000
	s_cselect_b32 s13, s12, s2
	s_lshl_b32 s4, s2, 12
	s_add_u32 s4, s24, s4
	s_addc_u32 s5, s25, 0
	s_lshl_b32 s6, s13, 12
	s_add_u32 s6, s24, s6
	s_addc_u32 s7, s25, 0
	global_load_dwordx4 v[48:51], v0, s[4:5] offset:0
	global_load_dwordx4 v[52:55], v0, s[4:5] offset:16
	global_load_dwordx4 v[56:59], v0, s[4:5] offset:2048
	global_load_dwordx4 v[60:63], v0, s[4:5] offset:2064
	global_load_dwordx4 v[64:67], v0, s[6:7] offset:0
	global_load_dwordx4 v[68:71], v0, s[6:7] offset:16
	global_load_dwordx4 v[72:75], v0, s[6:7] offset:2048
	global_load_dwordx4 v[76:79], v0, s[6:7] offset:2064
	s_waitcnt vmcnt(0)
	s_branch .Llna2_enter

.LBB0_1476:
	s_cmp_lt_i32 s28, 17
	s_cselect_b64 s[0:1], -1, 0
	s_cmp_gt_i32 s29, 16
	s_cselect_b64 s[2:3], -1, 0
	s_and_b64 s[0:1], s[0:1], s[2:3]
	s_andn2_b64 vcc, exec, s[0:1]
	s_cbranch_vccnz .LBB0_1542
	s_mov_b64 s[8:9], exec
	v_readlane_b32 s0, v254, 4
	v_lshrrev_b32_e32 v0, 6, v200
	s_lshl_b32 s3, s30, 3
	v_readfirstlane_b32 s2, v0
	v_mbcnt_lo_u32_b32 v0, -1, 0
	v_mbcnt_hi_u32_b32 v0, -1, v0
	s_add_i32 s2, s2, s0
	s_cmp_ge_i32 s2, 0x10000
	s_cbranch_scc1 .Llnb1_done
	v_lshlrev_b32_e32 v1, 4, v0
	v_lshlrev_b32_e32 v0, 5, v0
	s_add_u32 s4, s36, 4096
	s_addc_u32 s5, s37, 0
	s_add_u32 s6, s38, 4096
	s_addc_u32 s7, s39, 0
	global_load_dwordx4 v[80:83], v0, s[4:5] offset:0
	global_load_dwordx4 v[84:87], v0, s[4:5] offset:16
	global_load_dwordx4 v[88:91], v0, s[4:5] offset:2048
	global_load_dwordx4 v[92:95], v0, s[4:5] offset:2064
	global_load_dwordx4 v[96:99], v0, s[6:7] offset:0
	global_load_dwordx4 v[100:103], v0, s[6:7] offset:16
	global_load_dwordx4 v[104:107], v0, s[6:7] offset:2048
	global_load_dwordx4 v[108:111], v0, s[6:7] offset:2064
	s_add_u32 s10, s26, 0x6000000
	s_addc_u32 s11, s27, 0
	v_mov_b32_e32 v112, 0x3727c5ac
	s_add_i32 s12, s2, s3
	s_cmp_lt_i32 s12, 0x10000
	s_cselect_b32 s13, s12, s2
	s_lshl_b32 s4, s2, 12
	s_add_u32 s4, s24, s4
	s_addc_u32 s5, s25, 0
	s_lshl_b32 s6, s13, 12
	s_add_u32 s6, s24, s6
	s_addc_u32 s7, s25, 0
	global_load_dwordx4 v[48:51], v0, s[4:5] offset:0
	global_load_dwordx4 v[52:55], v0, s[4:5] offset:16
	global_load_dwordx4 v[56:59], v0, s[4:5] offset:2048
	global_load_dwordx4 v[60:63], v0, s[4:5] offset:2064
	global_load_dwordx4 v[64:67], v0, s[6:7] offset:0
	global_load_dwordx4 v[68:71], v0, s[6:7] offset:16
	global_load_dwordx4 v[72:75], v0, s[6:7] offset:2048
	global_load_dwordx4 v[76:79], v0, s[6:7] offset:2064
	s_waitcnt vmcnt(0)
	s_branch .Llnb1_enter

.LBB0_1765:
	s_cmp_lt_i32 s28, 21
	s_cselect_b64 s[0:1], -1, 0
	s_cmp_gt_i32 s29, 20
	s_cselect_b64 s[2:3], -1, 0
	s_and_b64 s[0:1], s[0:1], s[2:3]
	s_andn2_b64 vcc, exec, s[0:1]
	s_cbranch_vccnz .LBB0_1833
	s_mov_b64 s[10:11], exec
	v_readlane_b32 s0, v254, 4
	v_lshrrev_b32_e32 v0, 6, v200
	s_lshl_b32 s3, s30, 3
	v_readfirstlane_b32 s2, v0
	v_mbcnt_lo_u32_b32 v0, -1, 0
	v_mbcnt_hi_u32_b32 v0, -1, v0
	s_add_i32 s2, s2, s0
	s_cmp_ge_i32 s2, 0x10000
	s_cbranch_scc1 .Llnb2_done
	v_lshlrev_b32_e32 v1, 4, v0
	v_lshlrev_b32_e32 v0, 5, v0
	s_add_u32 s4, s40, 4096
	s_addc_u32 s5, s41, 0
	s_add_u32 s6, s42, 4096
	s_addc_u32 s7, s43, 0
	global_load_dwordx4 v[80:83], v0, s[4:5] offset:0
	global_load_dwordx4 v[84:87], v0, s[4:5] offset:16
	global_load_dwordx4 v[88:91], v0, s[4:5] offset:2048
	global_load_dwordx4 v[92:95], v0, s[4:5] offset:2064
	global_load_dwordx4 v[96:99], v0, s[6:7] offset:0
	global_load_dwordx4 v[100:103], v0, s[6:7] offset:16
	global_load_dwordx4 v[104:107], v0, s[6:7] offset:2048
	global_load_dwordx4 v[108:111], v0, s[6:7] offset:2064
	v_mov_b32_e32 v112, 0x3727c5ac
	s_add_i32 s12, s2, s3
	s_cmp_lt_i32 s12, 0x10000
	s_cselect_b32 s13, s12, s2
	s_lshl_b32 s4, s2, 12
	s_add_u32 s4, s24, s4
	s_addc_u32 s5, s25, 0
	s_lshl_b32 s6, s13, 12
	s_add_u32 s6, s24, s6
	s_addc_u32 s7, s25, 0
	global_load_dwordx4 v[48:51], v0, s[4:5] offset:0
	global_load_dwordx4 v[52:55], v0, s[4:5] offset:16
	global_load_dwordx4 v[56:59], v0, s[4:5] offset:2048
	global_load_dwordx4 v[60:63], v0, s[4:5] offset:2064
	global_load_dwordx4 v[64:67], v0, s[6:7] offset:0
	global_load_dwordx4 v[68:71], v0, s[6:7] offset:16
	global_load_dwordx4 v[72:75], v0, s[6:7] offset:2048
	global_load_dwordx4 v[76:79], v0, s[6:7] offset:2064
	s_waitcnt vmcnt(0)
	s_branch .Llnb2_enter

.Llnb2_nopf:
	v_add_f32_e32 v113, v16, v20
	v_add_f32_e32 v114, v17, v21
	v_add_f32_e32 v115, v18, v22
	v_add_f32_e32 v116, v19, v23
	v_add_f32_e32 v117, v32, v36
	v_add_f32_e32 v118, v33, v37
	v_add_f32_e32 v119, v34, v38
	v_add_f32_e32 v120, v35, v39
	v_add_f32_e32 v113, v113, v24
	v_add_f32_e32 v113, v113, v28
	v_add_f32_e32 v114, v114, v25
	v_add_f32_e32 v114, v114, v29
	v_add_f32_e32 v115, v115, v26
	v_add_f32_e32 v115, v115, v30
	v_add_f32_e32 v116, v116, v27
	v_add_f32_e32 v116, v116, v31
	v_add_f32_e32 v117, v117, v40
	v_add_f32_e32 v117, v117, v44
	v_add_f32_e32 v118, v118, v41
	v_add_f32_e32 v118, v118, v45
	v_add_f32_e32 v119, v119, v42
	v_add_f32_e32 v119, v119, v46
	v_add_f32_e32 v120, v120, v43
	v_add_f32_e32 v120, v120, v47
	v_add_f32_e32 v113, v113, v114
	v_add_f32_e32 v115, v115, v116
	v_add_f32_e32 v117, v117, v118
	v_add_f32_e32 v119, v119, v120
	v_add_f32_e32 v113, v113, v115
	v_add_f32_e32 v117, v117, v119
	s_nop 1
	v_add_f32_dpp v113, v113, v113 quad_perm:[1,0,3,2] row_mask:0xf bank_mask:0xf
	v_add_f32_dpp v117, v117, v117 quad_perm:[1,0,3,2] row_mask:0xf bank_mask:0xf
	s_nop 1
	v_add_f32_dpp v113, v113, v113 quad_perm:[2,3,0,1] row_mask:0xf bank_mask:0xf
	v_add_f32_dpp v117, v117, v117 quad_perm:[2,3,0,1] row_mask:0xf bank_mask:0xf
	s_nop 1
	v_add_f32_dpp v113, v113, v113 row_half_mirror row_mask:0xf bank_mask:0xf
	v_add_f32_dpp v117, v117, v117 row_half_mirror row_mask:0xf bank_mask:0xf
	s_nop 1
	v_add_f32_dpp v113, v113, v113 row_mirror row_mask:0xf bank_mask:0xf
	v_add_f32_dpp v117, v117, v117 row_mirror row_mask:0xf bank_mask:0xf
	s_nop 1
	v_readlane_b32 s4, v113, 0
	v_readlane_b32 s5, v113, 16
	v_readlane_b32 s6, v113, 32
	v_readlane_b32 s7, v113, 48
	v_readlane_b32 s12, v117, 0
	v_readlane_b32 s13, v117, 16
	v_readlane_b32 s0, v117, 32
	v_readlane_b32 s1, v117, 48
	s_nop 1
	v_mov_b32_e32 v113, s4
	v_mov_b32_e32 v117, s12
	v_add_f32_e32 v113, s5, v113
	v_add_f32_e32 v117, s13, v117
	v_add_f32_e32 v113, s6, v113
	v_add_f32_e32 v117, s0, v117
	v_add_f32_e32 v113, s7, v113
	v_add_f32_e32 v117, s1, v117
	v_fmamk_f32 v16, v113, 0xba800000, v16
	v_fmamk_f32 v17, v113, 0xba800000, v17
	v_fmamk_f32 v18, v113, 0xba800000, v18
	v_fmamk_f32 v19, v113, 0xba800000, v19
	v_fmamk_f32 v20, v113, 0xba800000, v20
	v_fmamk_f32 v21, v113, 0xba800000, v21
	v_fmamk_f32 v22, v113, 0xba800000, v22
	v_fmamk_f32 v23, v113, 0xba800000, v23
	v_fmamk_f32 v24, v113, 0xba800000, v24
	v_fmamk_f32 v25, v113, 0xba800000, v25
	v_fmamk_f32 v26, v113, 0xba800000, v26
	v_fmamk_f32 v27, v113, 0xba800000, v27
	v_fmamk_f32 v28, v113, 0xba800000, v28
	v_fmamk_f32 v29, v113, 0xba800000, v29
	v_fmamk_f32 v30, v113, 0xba800000, v30
	v_fmamk_f32 v31, v113, 0xba800000, v31
	v_fmamk_f32 v32, v117, 0xba800000, v32
	v_fmamk_f32 v33, v117, 0xba800000, v33
	v_fmamk_f32 v34, v117, 0xba800000, v34
	v_fmamk_f32 v35, v117, 0xba800000, v35
	v_fmamk_f32 v36, v117, 0xba800000, v36
	v_fmamk_f32 v37, v117, 0xba800000, v37
	v_fmamk_f32 v38, v117, 0xba800000, v38
	v_fmamk_f32 v39, v117, 0xba800000, v39
	v_fmamk_f32 v40, v117, 0xba800000, v40
	v_fmamk_f32 v41, v117, 0xba800000, v41
	v_fmamk_f32 v42, v117, 0xba800000, v42
	v_fmamk_f32 v43, v117, 0xba800000, v43
	v_fmamk_f32 v44, v117, 0xba800000, v44
	v_fmamk_f32 v45, v117, 0xba800000, v45
	v_fmamk_f32 v46, v117, 0xba800000, v46
	v_fmamk_f32 v47, v117, 0xba800000, v47
	v_mul_f32_e32 v113, v16, v16
	v_mul_f32_e32 v114, v17, v17
	v_mul_f32_e32 v115, v18, v18
	v_mul_f32_e32 v116, v19, v19
	v_mul_f32_e32 v117, v32, v32
	v_mul_f32_e32 v118, v33, v33
	v_mul_f32_e32 v119, v34, v34
	v_mul_f32_e32 v120, v35, v35
	v_fmac_f32_e32 v113, v20, v20
	v_fmac_f32_e32 v113, v24, v24
	v_fmac_f32_e32 v113, v28, v28
	v_fmac_f32_e32 v114, v21, v21
	v_fmac_f32_e32 v114, v25, v25
	v_fmac_f32_e32 v114, v29, v29
	v_fmac_f32_e32 v115, v22, v22
	v_fmac_f32_e32 v115, v26, v26
	v_fmac_f32_e32 v115, v30, v30
	v_fmac_f32_e32 v116, v23, v23
	v_fmac_f32_e32 v116, v27, v27
	v_fmac_f32_e32 v116, v31, v31
	v_fmac_f32_e32 v117, v36, v36
	v_fmac_f32_e32 v117, v40, v40
	v_fmac_f32_e32 v117, v44, v44
	v_fmac_f32_e32 v118, v37, v37
	v_fmac_f32_e32 v118, v41, v41
	v_fmac_f32_e32 v118, v45, v45
	v_fmac_f32_e32 v119, v38, v38
	v_fmac_f32_e32 v119, v42, v42
	v_fmac_f32_e32 v119, v46, v46
	v_fmac_f32_e32 v120, v39, v39
	v_fmac_f32_e32 v120, v43, v43
	v_fmac_f32_e32 v120, v47, v47
	v_add_f32_e32 v113, v113, v114
	v_add_f32_e32 v115, v115, v116
	v_add_f32_e32 v117, v117, v118
	v_add_f32_e32 v119, v119, v120
	v_add_f32_e32 v113, v113, v115
	v_add_f32_e32 v117, v117, v119
	s_nop 1
	v_add_f32_dpp v113, v113, v113 quad_perm:[1,0,3,2] row_mask:0xf bank_mask:0xf
	v_add_f32_dpp v117, v117, v117 quad_perm:[1,0,3,2] row_mask:0xf bank_mask:0xf
	s_nop 1
	v_add_f32_dpp v113, v113, v113 quad_perm:[2,3,0,1] row_mask:0xf bank_mask:0xf
	v_add_f32_dpp v117, v117, v117 quad_perm:[2,3,0,1] row_mask:0xf bank_mask:0xf
	s_nop 1
	v_add_f32_dpp v113, v113, v113 row_half_mirror row_mask:0xf bank_mask:0xf
	v_add_f32_dpp v117, v117, v117 row_half_mirror row_mask:0xf bank_mask:0xf
	s_nop 1
	v_add_f32_dpp v113, v113, v113 row_mirror row_mask:0xf bank_mask:0xf
	v_add_f32_dpp v117, v117, v117 row_mirror row_mask:0xf bank_mask:0xf
	s_nop 1
	v_readlane_b32 s4, v113, 0
	v_readlane_b32 s5, v113, 16
	v_readlane_b32 s6, v113, 32
	v_readlane_b32 s7, v113, 48
	v_readlane_b32 s12, v117, 0
	v_readlane_b32 s13, v117, 16
	v_readlane_b32 s0, v117, 32
	v_readlane_b32 s1, v117, 48
	s_nop 1
	v_mov_b32_e32 v113, s4
	v_mov_b32_e32 v117, s12
	v_add_f32_e32 v113, s5, v113
	v_add_f32_e32 v117, s13, v117
	v_add_f32_e32 v113, s6, v113
	v_add_f32_e32 v117, s0, v117
	v_add_f32_e32 v113, s7, v113
	v_add_f32_e32 v117, s1, v117
	v_fmamk_f32 v113, v113, 0x3a800000, v112
	v_fmamk_f32 v117, v117, 0x3a800000, v112
	v_rsq_f32_e32 v113, v113
	v_rsq_f32_e32 v117, v117
	s_nop 0
	v_mul_f32_e32 v16, v16, v113
	v_mul_f32_e32 v17, v17, v113
	v_mul_f32_e32 v18, v18, v113
	v_mul_f32_e32 v19, v19, v113
	v_mul_f32_e32 v20, v20, v113
	v_mul_f32_e32 v21, v21, v113
	v_mul_f32_e32 v22, v22, v113
	v_mul_f32_e32 v23, v23, v113
	v_mul_f32_e32 v24, v24, v113
	v_mul_f32_e32 v25, v25, v113
	v_mul_f32_e32 v26, v26, v113
	v_mul_f32_e32 v27, v27, v113
	v_mul_f32_e32 v28, v28, v113
	v_mul_f32_e32 v29, v29, v113
	v_mul_f32_e32 v30, v30, v113
	v_mul_f32_e32 v31, v31, v113
	v_fma_f32 v16, v16, v80, v96
	v_fma_f32 v17, v17, v81, v97
	v_fma_f32 v18, v18, v82, v98
	v_fma_f32 v19, v19, v83, v99
	v_fma_f32 v20, v20, v84, v100
	v_fma_f32 v21, v21, v85, v101
	v_fma_f32 v22, v22, v86, v102
	v_fma_f32 v23, v23, v87, v103
	v_fma_f32 v24, v24, v88, v104
	v_fma_f32 v25, v25, v89, v105
	v_fma_f32 v26, v26, v90, v106
	v_fma_f32 v27, v27, v91, v107
	v_fma_f32 v28, v28, v92, v108
	v_fma_f32 v29, v29, v93, v109
	v_fma_f32 v30, v30, v94, v110
	v_fma_f32 v31, v31, v95, v111
	v_mul_f32_e32 v32, v32, v117
	v_mul_f32_e32 v33, v33, v117
	v_mul_f32_e32 v34, v34, v117
	v_mul_f32_e32 v35, v35, v117
	v_mul_f32_e32 v36, v36, v117
	v_mul_f32_e32 v37, v37, v117
	v_mul_f32_e32 v38, v38, v117
	v_mul_f32_e32 v39, v39, v117
	v_mul_f32_e32 v40, v40, v117
	v_mul_f32_e32 v41, v41, v117
	v_mul_f32_e32 v42, v42, v117
	v_mul_f32_e32 v43, v43, v117
	v_mul_f32_e32 v44, v44, v117
	v_mul_f32_e32 v45, v45, v117
	v_mul_f32_e32 v46, v46, v117
	v_mul_f32_e32 v47, v47, v117
	v_fma_f32 v32, v32, v80, v96
	v_fma_f32 v33, v33, v81, v97
	v_fma_f32 v34, v34, v82, v98
	v_fma_f32 v35, v35, v83, v99
	v_fma_f32 v36, v36, v84, v100
	v_fma_f32 v37, v37, v85, v101
	v_fma_f32 v38, v38, v86, v102
	v_fma_f32 v39, v39, v87, v103
	v_fma_f32 v40, v40, v88, v104
	v_fma_f32 v41, v41, v89, v105
	v_fma_f32 v42, v42, v90, v106
	v_fma_f32 v43, v43, v91, v107
	v_fma_f32 v44, v44, v92, v108
	v_fma_f32 v45, v45, v93, v109
	v_fma_f32 v46, v46, v94, v110
	v_fma_f32 v47, v47, v95, v111
	s_lshl_b32 s4, s8, 12
	s_add_u32 s4, s24, s4
	s_addc_u32 s5, s25, 0
	global_store_dwordx4 v0, v[16:19], s[4:5] offset:0
	global_store_dwordx4 v0, v[20:23], s[4:5] offset:16
	global_store_dwordx4 v0, v[24:27], s[4:5] offset:2048
	global_store_dwordx4 v0, v[28:31], s[4:5] offset:2064
	s_cmp_ge_i32 s9, 0x10000
	s_cbranch_scc1 .Llnb2_st1
	s_lshl_b32 s6, s9, 12
	s_add_u32 s6, s24, s6
	s_addc_u32 s7, s25, 0
	global_store_dwordx4 v0, v[32:35], s[6:7] offset:0
	global_store_dwordx4 v0, v[36:39], s[6:7] offset:16
	global_store_dwordx4 v0, v[40:43], s[6:7] offset:2048
	global_store_dwordx4 v0, v[44:47], s[6:7] offset:2064
